# stack: v18 + RG-LRU gate-gelu precompute in the look-back window + publisher-aware slot waits + batched row-statistics exchange polls (P4, P6)
# speedup vs baseline: 1.0071x; 1.0063x over previous
.LBB0_306:
	s_waitcnt vmcnt(0)
	v_mov_b32_e32 v101, v196
	v_lshl_add_u64 v[100:101], s[18:19], 0, v[100:101]
	v_lshlrev_b64 v[98:99], 11, v[98:99]
	v_add_f32_e32 v103, v164, v116
	v_mul_f32_e32 v104, v163, v178
	v_fmac_f32_e32 v103, v104, v102
	v_mul_f32_e32 v103, v188, v103
	v_lshl_add_u64 v[104:105], v[100:101], 0, v[98:99]
	v_cvt_pk_bf16_f32 v103, v103, v196
	global_store_short v[104:105], v103, off
	v_fmac_f32_e32 v165, v166, v117
	v_mul_f32_e32 v106, v166, v178
	v_fmac_f32_e32 v165, v106, v102
	v_mul_f32_e32 v103, v189, v165
	v_or_b32_e32 v104, 0x800, v98
	v_mov_b32_e32 v105, v99
	v_lshl_add_u64 v[104:105], v[100:101], 0, v[104:105]
	v_cvt_pk_bf16_f32 v103, v103, v196
	global_store_short v[104:105], v103, off
	v_fmac_f32_e32 v167, v169, v117
	v_mul_f32_e32 v107, v169, v178
	v_fmac_f32_e32 v167, v107, v102
	v_mul_f32_e32 v103, v190, v167
	v_or_b32_e32 v104, 0x1000, v98
	v_mov_b32_e32 v105, v99
	v_lshl_add_u64 v[104:105], v[100:101], 0, v[104:105]
	v_cvt_pk_bf16_f32 v103, v103, v196
	global_store_short v[104:105], v103, off
	v_fmac_f32_e32 v168, v171, v117
	v_mul_f32_e32 v108, v171, v178
	v_fmac_f32_e32 v168, v108, v102
	v_mul_f32_e32 v103, v191, v168
	v_or_b32_e32 v104, 0x1800, v98
	v_mov_b32_e32 v105, v99
	v_lshl_add_u64 v[104:105], v[100:101], 0, v[104:105]
	v_cvt_pk_bf16_f32 v103, v103, v196
	global_store_short v[104:105], v103, off
	v_fmac_f32_e32 v170, v173, v117
	v_mul_f32_e32 v109, v173, v178
	v_fmac_f32_e32 v170, v109, v102
	v_mul_f32_e32 v103, v192, v170
	v_or_b32_e32 v104, 0x2000, v98
	v_mov_b32_e32 v105, v99
	v_lshl_add_u64 v[104:105], v[100:101], 0, v[104:105]
	v_cvt_pk_bf16_f32 v103, v103, v196
	global_store_short v[104:105], v103, off
	v_fmac_f32_e32 v172, v175, v117
	v_mul_f32_e32 v110, v175, v178
	v_fmac_f32_e32 v172, v110, v102
	v_mul_f32_e32 v103, v193, v172
	v_or_b32_e32 v104, 0x2800, v98
	v_mov_b32_e32 v105, v99
	v_lshl_add_u64 v[104:105], v[100:101], 0, v[104:105]
	v_cvt_pk_bf16_f32 v103, v103, v196
	global_store_short v[104:105], v103, off
	v_fmac_f32_e32 v174, v176, v117
	v_mul_f32_e32 v111, v176, v178
	v_fmac_f32_e32 v174, v111, v102
	v_mul_f32_e32 v103, v194, v174
	v_or_b32_e32 v104, 0x3000, v98
	v_mov_b32_e32 v105, v99
	v_lshl_add_u64 v[104:105], v[100:101], 0, v[104:105]
	v_cvt_pk_bf16_f32 v103, v103, v196
	global_store_short v[104:105], v103, off
	v_fmac_f32_e32 v115, v177, v102
	v_mul_f32_e32 v103, v195, v115
	v_or_b32_e32 v104, 0x3800, v98
	v_mov_b32_e32 v105, v99
	v_lshl_add_u64 v[104:105], v[100:101], 0, v[104:105]
	v_cvt_pk_bf16_f32 v103, v103, v196
	global_store_short v[104:105], v103, off
	s_and_b64 vcc, exec, s[16:17]
	s_mov_b32 s40, s15
	s_cbranch_vccnz .LBB0_360

.LBB0_331:
	v_fmac_f32_e32 v115, v114, v117
	v_mul_f32_e32 v177, v114, v178
	s_and_saveexec_b64 s[0:1], s[52:53]
	s_cbranch_execz .LBB0_340
	s_add_i32 s68, s73, s33
	s_ashr_i32 s69, s68, 31
	s_lshl_b64 s[68:69], s[68:69], 12
	s_add_u32 s68, s36, s68
	v_or_b32_e32 v114, 1, v177
	s_addc_u32 s69, s37, s69
	global_store_dwordx2 v112, v[114:115], s[68:69] sc1
	s_or_b64 exec, exec, s[0:1]
	s_waitcnt vmcnt(1)
	v_lshlrev_b32_e32 v179, 16, v101
	v_mul_f32_e32 v222, 0x3d372713, v179
	v_mul_f32_e32 v222, v222, v179
	v_fma_f32 v222, v222, v179, v179
	v_mul_f32_e32 v222, 0x3f4c422a, v222
	v_add_f32_e32 v222, v222, v222
	v_mul_f32_e32 v222, 0x3fb8aa3b, v222
	v_exp_f32_e32 v222, v222
	v_mul_f32_e32 v179, 0.5, v179
	v_add_f32_e32 v222, 1.0, v222
	v_rcp_f32_e32 v222, v222
	s_nop 0
	v_fma_f32 v222, v222, -2.0, 1.0
	v_add_f32_e32 v222, 1.0, v222
	v_mul_f32_e32 v188, v179, v222
	v_lshlrev_b32_e32 v179, 16, v162
	v_mul_f32_e32 v222, 0x3d372713, v179
	v_mul_f32_e32 v222, v222, v179
	v_fma_f32 v222, v222, v179, v179
	v_mul_f32_e32 v222, 0x3f4c422a, v222
	v_add_f32_e32 v222, v222, v222
	v_mul_f32_e32 v222, 0x3fb8aa3b, v222
	v_exp_f32_e32 v222, v222
	v_mul_f32_e32 v179, 0.5, v179
	v_add_f32_e32 v222, 1.0, v222
	v_rcp_f32_e32 v222, v222
	s_nop 0
	v_fma_f32 v222, v222, -2.0, 1.0
	v_add_f32_e32 v222, 1.0, v222
	v_mul_f32_e32 v189, v179, v222
	v_lshlrev_b32_e32 v179, 16, v161
	v_mul_f32_e32 v222, 0x3d372713, v179
	v_mul_f32_e32 v222, v222, v179
	v_fma_f32 v222, v222, v179, v179
	v_mul_f32_e32 v222, 0x3f4c422a, v222
	v_add_f32_e32 v222, v222, v222
	v_mul_f32_e32 v222, 0x3fb8aa3b, v222
	v_exp_f32_e32 v222, v222
	v_mul_f32_e32 v179, 0.5, v179
	v_add_f32_e32 v222, 1.0, v222
	v_rcp_f32_e32 v222, v222
	s_nop 0
	v_fma_f32 v222, v222, -2.0, 1.0
	v_add_f32_e32 v222, 1.0, v222
	v_mul_f32_e32 v190, v179, v222
	v_lshlrev_b32_e32 v179, 16, v160
	v_mul_f32_e32 v222, 0x3d372713, v179
	v_mul_f32_e32 v222, v222, v179
	v_fma_f32 v222, v222, v179, v179
	v_mul_f32_e32 v222, 0x3f4c422a, v222
	v_add_f32_e32 v222, v222, v222
	v_mul_f32_e32 v222, 0x3fb8aa3b, v222
	v_exp_f32_e32 v222, v222
	v_mul_f32_e32 v179, 0.5, v179
	v_add_f32_e32 v222, 1.0, v222
	v_rcp_f32_e32 v222, v222
	s_nop 0
	v_fma_f32 v222, v222, -2.0, 1.0
	v_add_f32_e32 v222, 1.0, v222
	v_mul_f32_e32 v191, v179, v222
	v_lshlrev_b32_e32 v179, 16, v159
	v_mul_f32_e32 v222, 0x3d372713, v179
	v_mul_f32_e32 v222, v222, v179
	v_fma_f32 v222, v222, v179, v179
	v_mul_f32_e32 v222, 0x3f4c422a, v222
	v_add_f32_e32 v222, v222, v222
	v_mul_f32_e32 v222, 0x3fb8aa3b, v222
	v_exp_f32_e32 v222, v222
	v_mul_f32_e32 v179, 0.5, v179
	v_add_f32_e32 v222, 1.0, v222
	v_rcp_f32_e32 v222, v222
	s_nop 0
	v_fma_f32 v222, v222, -2.0, 1.0
	v_add_f32_e32 v222, 1.0, v222
	v_mul_f32_e32 v192, v179, v222
	v_lshlrev_b32_e32 v179, 16, v158
	v_mul_f32_e32 v222, 0x3d372713, v179
	v_mul_f32_e32 v222, v222, v179
	v_fma_f32 v222, v222, v179, v179
	v_mul_f32_e32 v222, 0x3f4c422a, v222
	v_add_f32_e32 v222, v222, v222
	v_mul_f32_e32 v222, 0x3fb8aa3b, v222
	v_exp_f32_e32 v222, v222
	v_mul_f32_e32 v179, 0.5, v179
	v_add_f32_e32 v222, 1.0, v222
	v_rcp_f32_e32 v222, v222
	s_nop 0
	v_fma_f32 v222, v222, -2.0, 1.0
	v_add_f32_e32 v222, 1.0, v222
	v_mul_f32_e32 v193, v179, v222
	v_lshlrev_b32_e32 v179, 16, v157
	v_mul_f32_e32 v222, 0x3d372713, v179
	v_mul_f32_e32 v222, v222, v179
	v_fma_f32 v222, v222, v179, v179
	v_mul_f32_e32 v222, 0x3f4c422a, v222
	v_add_f32_e32 v222, v222, v222
	v_mul_f32_e32 v222, 0x3fb8aa3b, v222
	v_exp_f32_e32 v222, v222
	v_mul_f32_e32 v179, 0.5, v179
	v_add_f32_e32 v222, 1.0, v222
	v_rcp_f32_e32 v222, v222
	s_nop 0
	v_fma_f32 v222, v222, -2.0, 1.0
	v_add_f32_e32 v222, 1.0, v222
	v_mul_f32_e32 v194, v179, v222
	v_lshlrev_b32_e32 v179, 16, v156
	v_mul_f32_e32 v222, 0x3d372713, v179
	v_mul_f32_e32 v222, v222, v179
	v_fma_f32 v222, v222, v179, v179
	v_mul_f32_e32 v222, 0x3f4c422a, v222
	v_add_f32_e32 v222, v222, v222
	v_mul_f32_e32 v222, 0x3fb8aa3b, v222
	v_exp_f32_e32 v222, v222
	v_mul_f32_e32 v179, 0.5, v179
	v_add_f32_e32 v222, 1.0, v222
	v_rcp_f32_e32 v222, v222
	s_nop 0
	v_fma_f32 v222, v222, -2.0, 1.0
	v_add_f32_e32 v222, 1.0, v222
	v_mul_f32_e32 v195, v179, v222
	s_and_saveexec_b64 s[68:69], s[44:45]
	s_cbranch_execnz .LBB0_341

.LBB0_340:
	s_or_b64 exec, exec, s[0:1]
	s_waitcnt vmcnt(0)
	v_lshlrev_b32_e32 v179, 16, v101
	v_mul_f32_e32 v222, 0x3d372713, v179
	v_mul_f32_e32 v222, v222, v179
	v_fma_f32 v222, v222, v179, v179
	v_mul_f32_e32 v222, 0x3f4c422a, v222
	v_add_f32_e32 v222, v222, v222
	v_mul_f32_e32 v222, 0x3fb8aa3b, v222
	v_exp_f32_e32 v222, v222
	v_mul_f32_e32 v179, 0.5, v179
	v_add_f32_e32 v222, 1.0, v222
	v_rcp_f32_e32 v222, v222
	s_nop 0
	v_fma_f32 v222, v222, -2.0, 1.0
	v_add_f32_e32 v222, 1.0, v222
	v_mul_f32_e32 v188, v179, v222
	v_lshlrev_b32_e32 v179, 16, v162
	v_mul_f32_e32 v222, 0x3d372713, v179
	v_mul_f32_e32 v222, v222, v179
	v_fma_f32 v222, v222, v179, v179
	v_mul_f32_e32 v222, 0x3f4c422a, v222
	v_add_f32_e32 v222, v222, v222
	v_mul_f32_e32 v222, 0x3fb8aa3b, v222
	v_exp_f32_e32 v222, v222
	v_mul_f32_e32 v179, 0.5, v179
	v_add_f32_e32 v222, 1.0, v222
	v_rcp_f32_e32 v222, v222
	s_nop 0
	v_fma_f32 v222, v222, -2.0, 1.0
	v_add_f32_e32 v222, 1.0, v222
	v_mul_f32_e32 v189, v179, v222
	v_lshlrev_b32_e32 v179, 16, v161
	v_mul_f32_e32 v222, 0x3d372713, v179
	v_mul_f32_e32 v222, v222, v179
	v_fma_f32 v222, v222, v179, v179
	v_mul_f32_e32 v222, 0x3f4c422a, v222
	v_add_f32_e32 v222, v222, v222
	v_mul_f32_e32 v222, 0x3fb8aa3b, v222
	v_exp_f32_e32 v222, v222
	v_mul_f32_e32 v179, 0.5, v179
	v_add_f32_e32 v222, 1.0, v222
	v_rcp_f32_e32 v222, v222
	s_nop 0
	v_fma_f32 v222, v222, -2.0, 1.0
	v_add_f32_e32 v222, 1.0, v222
	v_mul_f32_e32 v190, v179, v222
	v_lshlrev_b32_e32 v179, 16, v160
	v_mul_f32_e32 v222, 0x3d372713, v179
	v_mul_f32_e32 v222, v222, v179
	v_fma_f32 v222, v222, v179, v179
	v_mul_f32_e32 v222, 0x3f4c422a, v222
	v_add_f32_e32 v222, v222, v222
	v_mul_f32_e32 v222, 0x3fb8aa3b, v222
	v_exp_f32_e32 v222, v222
	v_mul_f32_e32 v179, 0.5, v179
	v_add_f32_e32 v222, 1.0, v222
	v_rcp_f32_e32 v222, v222
	s_nop 0
	v_fma_f32 v222, v222, -2.0, 1.0
	v_add_f32_e32 v222, 1.0, v222
	v_mul_f32_e32 v191, v179, v222
	v_lshlrev_b32_e32 v179, 16, v159
	v_mul_f32_e32 v222, 0x3d372713, v179
	v_mul_f32_e32 v222, v222, v179
	v_fma_f32 v222, v222, v179, v179
	v_mul_f32_e32 v222, 0x3f4c422a, v222
	v_add_f32_e32 v222, v222, v222
	v_mul_f32_e32 v222, 0x3fb8aa3b, v222
	v_exp_f32_e32 v222, v222
	v_mul_f32_e32 v179, 0.5, v179
	v_add_f32_e32 v222, 1.0, v222
	v_rcp_f32_e32 v222, v222
	s_nop 0
	v_fma_f32 v222, v222, -2.0, 1.0
	v_add_f32_e32 v222, 1.0, v222
	v_mul_f32_e32 v192, v179, v222
	v_lshlrev_b32_e32 v179, 16, v158
	v_mul_f32_e32 v222, 0x3d372713, v179
	v_mul_f32_e32 v222, v222, v179
	v_fma_f32 v222, v222, v179, v179
	v_mul_f32_e32 v222, 0x3f4c422a, v222
	v_add_f32_e32 v222, v222, v222
	v_mul_f32_e32 v222, 0x3fb8aa3b, v222
	v_exp_f32_e32 v222, v222
	v_mul_f32_e32 v179, 0.5, v179
	v_add_f32_e32 v222, 1.0, v222
	v_rcp_f32_e32 v222, v222
	s_nop 0
	v_fma_f32 v222, v222, -2.0, 1.0
	v_add_f32_e32 v222, 1.0, v222
	v_mul_f32_e32 v193, v179, v222
	v_lshlrev_b32_e32 v179, 16, v157
	v_mul_f32_e32 v222, 0x3d372713, v179
	v_mul_f32_e32 v222, v222, v179
	v_fma_f32 v222, v222, v179, v179
	v_mul_f32_e32 v222, 0x3f4c422a, v222
	v_add_f32_e32 v222, v222, v222
	v_mul_f32_e32 v222, 0x3fb8aa3b, v222
	v_exp_f32_e32 v222, v222
	v_mul_f32_e32 v179, 0.5, v179
	v_add_f32_e32 v222, 1.0, v222
	v_rcp_f32_e32 v222, v222
	s_nop 0
	v_fma_f32 v222, v222, -2.0, 1.0
	v_add_f32_e32 v222, 1.0, v222
	v_mul_f32_e32 v194, v179, v222
	v_lshlrev_b32_e32 v179, 16, v156
	v_mul_f32_e32 v222, 0x3d372713, v179
	v_mul_f32_e32 v222, v222, v179
	v_fma_f32 v222, v222, v179, v179
	v_mul_f32_e32 v222, 0x3f4c422a, v222
	v_add_f32_e32 v222, v222, v222
	v_mul_f32_e32 v222, 0x3fb8aa3b, v222
	v_exp_f32_e32 v222, v222
	v_mul_f32_e32 v179, 0.5, v179
	v_add_f32_e32 v222, 1.0, v222
	v_rcp_f32_e32 v222, v222
	s_nop 0
	v_fma_f32 v222, v222, -2.0, 1.0
	v_add_f32_e32 v222, 1.0, v222
	v_mul_f32_e32 v195, v179, v222
	s_and_saveexec_b64 s[68:69], s[44:45]
	s_cbranch_execz .LBB0_333
